# w_out/down GEMM k-loop hand-pipelined: fragment double-buffering, LDS-DMA issues interleaved between MFMAs, m0 from SGPR base
# speedup vs baseline: 1.0284x; 1.0094x over previous
.LBB0_88:
	s_lshl_b32 s11, s16, 7
	s_and_b32 s27, s11, 0x1f80
	v_add_u32_e32 v5, s27, v86
	v_mad_i64_i32 v[2:3], s[38:39], v5, s13, 0
	s_lshl_b32 s11, s16, 1
	s_and_b32 s38, s11, 0xffffff80
	v_add_u32_e32 v4, s38, v86
	v_add_u32_e32 v14, 0, v87
	v_min_i32_e32 v6, 0x3ff, v4
	v_readfirstlane_b32 s11, v14
	v_add_u32_e32 v15, 0x8000, v14
	v_mad_i64_i32 v[6:7], s[40:41], v6, s13, 0
	v_lshl_add_u64 v[2:3], v[2:3], 1, v[66:67]
	s_mov_b32 m0, s11
	v_readfirstlane_b32 s11, v15
	v_add_u32_e32 v15, 0x1000, v14
	v_lshl_add_u64 v[6:7], v[6:7], 1, v[68:69]
	global_load_lds_dwordx4 v[2:3], off
	s_mov_b32 m0, s11
	v_readfirstlane_b32 s11, v15
	v_add_u32_e32 v8, 32, v4
	global_load_lds_dwordx4 v[6:7], off
	v_lshl_add_u64 v[6:7], v[2:3], 0, s[92:93]
	s_mov_b32 m0, s11
	v_min_i32_e32 v8, 0x3ff, v8
	global_load_lds_dwordx4 v[6:7], off
	v_add_u32_e32 v6, 0x9000, v14
	v_mad_i64_i32 v[8:9], s[40:41], v8, s13, 0
	v_readfirstlane_b32 s11, v6
	v_lshl_add_u64 v[8:9], v[8:9], 1, v[68:69]
	s_mov_b32 m0, s11
	s_mov_b32 s11, s93
	global_load_lds_dwordx4 v[8:9], off
	v_add_u32_e32 v8, 0x2000, v14
	v_lshl_add_u64 v[6:7], v[2:3], 0, s[10:11]
	v_readfirstlane_b32 s11, v8
	v_add_u32_e32 v10, 64, v4
	s_mov_b32 m0, s11
	v_min_i32_e32 v10, 0x3ff, v10
	global_load_lds_dwordx4 v[6:7], off
	v_add_u32_e32 v6, 0xa000, v14
	v_mad_i64_i32 v[10:11], s[40:41], v10, s13, 0
	v_readfirstlane_b32 s11, v6
	v_add_u32_e32 v6, 0x3000, v14
	v_lshl_add_u64 v[10:11], v[10:11], 1, v[68:69]
	s_mov_b32 m0, s11
	s_mov_b32 s37, s93
	v_readfirstlane_b32 s11, v6
	v_add_u32_e32 v12, 0x60, v4
	global_load_lds_dwordx4 v[10:11], off
	v_lshl_add_u64 v[2:3], v[2:3], 0, s[36:37]
	s_mov_b32 m0, s11
	v_min_i32_e32 v12, 0x3ff, v12
	global_load_lds_dwordx4 v[2:3], off
	v_add_u32_e32 v2, 0xb000, v14
	v_mad_i64_i32 v[12:13], s[40:41], v12, s13, 0
	v_readfirstlane_b32 s11, v2
	v_lshl_add_u64 v[12:13], v[12:13], 1, v[68:69]
	s_mov_b32 m0, s11
	v_mov_b64_e32 v[2:3], s[4:5]
	global_load_lds_dwordx4 v[12:13], off
	v_mad_i64_i32 v[70:71], s[40:41], s25, v5, v[2:3]
	v_lshlrev_b32_e32 v5, 1, v5
	v_add_u32_e32 v6, 64, v5
	v_mad_i64_i32 v[72:73], s[40:41], s13, v6, v[2:3]
	v_add_u32_e32 v6, 0x80, v5
	v_add_u32_e32 v5, 0xc0, v5
	v_mad_i64_i32 v[76:77], s[40:41], s13, v5, v[2:3]
	v_ashrrev_i32_e32 v5, 31, v4
	s_mov_b64 s[42:43], 0x3ff
	v_cmp_gt_i64_e32 vcc, s[42:43], v[4:5]
	v_mad_i64_i32 v[74:75], s[40:41], s13, v6, v[2:3]
	s_nop 0
	v_cndmask_b32_e32 v4, v199, v4, vcc
	v_mov_b64_e32 v[2:3], s[6:7]
	v_mad_i64_i32 v[78:79], s[40:41], s25, v4, v[2:3]
	v_add_u32_e32 v4, s38, v97
	v_ashrrev_i32_e32 v5, 31, v4
	v_cmp_gt_i64_e32 vcc, s[42:43], v[4:5]
	s_waitcnt vmcnt(0)
	s_movk_i32 s11, 0x4000
	s_waitcnt vmcnt(0) lgkmcnt(0)
	v_cndmask_b32_e32 v4, v199, v4, vcc
	v_mad_i64_i32 v[80:81], s[40:41], s25, v4, v[2:3]
	v_add_u32_e32 v4, s38, v98
	v_ashrrev_i32_e32 v5, 31, v4
	v_cmp_gt_i64_e32 vcc, s[42:43], v[4:5]
	s_barrier
	s_nop 0
	v_cndmask_b32_e32 v4, v199, v4, vcc
	v_mad_i64_i32 v[82:83], s[40:41], s25, v4, v[2:3]
	v_add_u32_e32 v4, s38, v99
	v_ashrrev_i32_e32 v5, 31, v4
	v_cmp_gt_i64_e32 vcc, s[42:43], v[4:5]
	s_nop 1
	v_cndmask_b32_e32 v4, v199, v4, vcc
	v_mad_i64_i32 v[84:85], s[40:41], s25, v4, v[2:3]
	v_mov_b32_e32 v2, 0
	v_mov_b32_e32 v3, v2
	v_mov_b32_e32 v4, v2
	v_mov_b32_e32 v5, v2
	v_mov_b32_e32 v6, v2
	v_mov_b32_e32 v7, v2
	v_mov_b32_e32 v8, v2
	v_mov_b32_e32 v9, v2
	v_mov_b32_e32 v10, v2
	v_mov_b32_e32 v11, v2
	v_mov_b32_e32 v12, v2
	v_mov_b32_e32 v13, v2
	v_mov_b32_e32 v14, v2
	v_mov_b32_e32 v15, v2
	v_mov_b32_e32 v16, v2
	v_mov_b32_e32 v17, v2
	v_mov_b32_e32 v18, v2
	v_mov_b32_e32 v19, v2
	v_mov_b32_e32 v20, v2
	v_mov_b32_e32 v21, v2
	v_mov_b32_e32 v22, v2
	v_mov_b32_e32 v23, v2
	v_mov_b32_e32 v24, v2
	v_mov_b32_e32 v25, v2
	v_mov_b32_e32 v26, v2
	v_mov_b32_e32 v27, v2
	v_mov_b32_e32 v28, v2
	v_mov_b32_e32 v29, v2
	v_mov_b32_e32 v30, v2
	v_mov_b32_e32 v31, v2
	v_mov_b32_e32 v32, v2
	v_mov_b32_e32 v33, v2
	v_mov_b32_e32 v34, v2
	v_mov_b32_e32 v35, v2
	v_mov_b32_e32 v36, v2
	v_mov_b32_e32 v37, v2
	v_mov_b32_e32 v38, v2
	v_mov_b32_e32 v39, v2
	v_mov_b32_e32 v40, v2
	v_mov_b32_e32 v41, v2
	v_mov_b32_e32 v42, v2
	v_mov_b32_e32 v43, v2
	v_mov_b32_e32 v44, v2
	v_mov_b32_e32 v45, v2
	v_mov_b32_e32 v46, v2
	v_mov_b32_e32 v47, v2
	v_mov_b32_e32 v48, v2
	v_mov_b32_e32 v49, v2
	v_mov_b32_e32 v50, v2
	v_mov_b32_e32 v51, v2
	v_mov_b32_e32 v52, v2
	v_mov_b32_e32 v53, v2
	v_mov_b32_e32 v54, v2
	v_mov_b32_e32 v55, v2
	v_mov_b32_e32 v56, v2
	v_mov_b32_e32 v57, v2
	v_mov_b32_e32 v58, v2
	v_mov_b32_e32 v59, v2
	v_mov_b32_e32 v60, v2
	v_mov_b32_e32 v61, v2
	v_mov_b32_e32 v62, v2
	v_mov_b32_e32 v63, v2
	v_mov_b32_e32 v64, v2
	v_mov_b32_e32 v65, v2
	v_readfirstlane_b32 s37, v87
	s_lshr_b32 s39, s22, 15
	s_sub_u32 s39, s39, 1
	v_lshl_add_u64 v[70:71], v[70:71], 0, v[130:131]
	v_lshl_add_u64 v[72:73], v[72:73], 0, v[130:131]
	v_lshl_add_u64 v[74:75], v[74:75], 0, v[130:131]
	v_lshl_add_u64 v[76:77], v[76:77], 0, v[130:131]
	v_lshl_add_u64 v[78:79], v[78:79], 0, v[130:131]
	v_lshl_add_u64 v[80:81], v[80:81], 0, v[130:131]
	v_lshl_add_u64 v[82:83], v[82:83], 0, v[130:131]
	v_lshl_add_u64 v[84:85], v[84:85], 0, v[130:131]
	v_add3_u32 v116, v88, v89, v90
	v_add_u32_e32 v120, v88, v92
	v_add3_u32 v117, v93, v89, v90
	v_add_u32_e32 v121, v93, v92
	v_add3_u32 v118, v94, v89, v90
	v_add_u32_e32 v122, v94, v92
	v_add3_u32 v119, v95, v89, v90
	v_add_u32_e32 v123, v95, v92
	ds_read_b128 v[132:135], v116
	ds_read_b128 v[136:139], v116 offset:4096
	ds_read_b128 v[140:143], v120 offset:32768
	ds_read_b128 v[144:147], v120 offset:40960
.Lg2_loop:
	ds_read_b128 v[148:151], v117
	ds_read_b128 v[152:155], v117 offset:4096
	ds_read_b128 v[156:159], v121 offset:32768
	ds_read_b128 v[160:163], v121 offset:40960
	s_waitcnt lgkmcnt(4)
	v_mfma_f32_32x32x16_bf16 v[50:65], v[132:135], v[140:143], v[50:65]
	s_add_u32 m0, s37, 0x4000
	s_nop 0
	global_load_lds_dwordx4 v[70:71], off
	v_lshl_add_u64 v[70:71], v[70:71], 0, s[98:99]
	v_mfma_f32_32x32x16_bf16 v[34:49], v[132:135], v[144:147], v[34:49]
	s_add_u32 m0, s37, 0xc000
	s_nop 0
	global_load_lds_dwordx4 v[78:79], off
	v_lshl_add_u64 v[78:79], v[78:79], 0, s[98:99]
	v_mfma_f32_32x32x16_bf16 v[18:33], v[136:139], v[140:143], v[18:33]
	s_add_u32 m0, s37, 0x5000
	s_nop 0
	global_load_lds_dwordx4 v[72:73], off
	v_lshl_add_u64 v[72:73], v[72:73], 0, s[98:99]
	v_mfma_f32_32x32x16_bf16 v[2:17], v[136:139], v[144:147], v[2:17]
	ds_read_b128 v[132:135], v118
	ds_read_b128 v[136:139], v118 offset:4096
	ds_read_b128 v[140:143], v122 offset:32768
	ds_read_b128 v[144:147], v122 offset:40960
	s_waitcnt lgkmcnt(4)
	v_mfma_f32_32x32x16_bf16 v[50:65], v[148:151], v[156:159], v[50:65]
	s_add_u32 m0, s37, 0xd000
	s_nop 0
	global_load_lds_dwordx4 v[80:81], off
	v_lshl_add_u64 v[80:81], v[80:81], 0, s[98:99]
	v_mfma_f32_32x32x16_bf16 v[34:49], v[148:151], v[160:163], v[34:49]
	s_add_u32 m0, s37, 0x6000
	s_nop 0
	global_load_lds_dwordx4 v[74:75], off
	v_lshl_add_u64 v[74:75], v[74:75], 0, s[98:99]
	v_mfma_f32_32x32x16_bf16 v[18:33], v[152:155], v[156:159], v[18:33]
	s_add_u32 m0, s37, 0xe000
	s_nop 0
	global_load_lds_dwordx4 v[82:83], off
	v_lshl_add_u64 v[82:83], v[82:83], 0, s[98:99]
	v_mfma_f32_32x32x16_bf16 v[2:17], v[152:155], v[160:163], v[2:17]
	ds_read_b128 v[148:151], v119
	ds_read_b128 v[152:155], v119 offset:4096
	ds_read_b128 v[156:159], v123 offset:32768
	ds_read_b128 v[160:163], v123 offset:40960
	s_waitcnt lgkmcnt(4)
	v_mfma_f32_32x32x16_bf16 v[50:65], v[132:135], v[140:143], v[50:65]
	s_add_u32 m0, s37, 0x7000
	s_nop 0
	global_load_lds_dwordx4 v[76:77], off
	v_lshl_add_u64 v[76:77], v[76:77], 0, s[98:99]
	v_mfma_f32_32x32x16_bf16 v[34:49], v[132:135], v[144:147], v[34:49]
	s_add_u32 m0, s37, 0xf000
	s_nop 0
	global_load_lds_dwordx4 v[84:85], off
	v_lshl_add_u64 v[84:85], v[84:85], 0, s[98:99]
	v_mfma_f32_32x32x16_bf16 v[18:33], v[136:139], v[140:143], v[18:33]
	v_mfma_f32_32x32x16_bf16 v[2:17], v[136:139], v[144:147], v[2:17]
	s_waitcnt vmcnt(0) lgkmcnt(0)
	s_barrier
	ds_read_b128 v[132:135], v116 offset:16384
	ds_read_b128 v[136:139], v116 offset:20480
	ds_read_b128 v[140:143], v120 offset:49152
	ds_read_b128 v[144:147], v120 offset:57344
	v_mfma_f32_32x32x16_bf16 v[50:65], v[148:151], v[156:159], v[50:65]
	v_mfma_f32_32x32x16_bf16 v[34:49], v[148:151], v[160:163], v[34:49]
	v_mfma_f32_32x32x16_bf16 v[18:33], v[152:155], v[156:159], v[18:33]
	v_mfma_f32_32x32x16_bf16 v[2:17], v[152:155], v[160:163], v[2:17]
	ds_read_b128 v[148:151], v117 offset:16384
	ds_read_b128 v[152:155], v117 offset:20480
	ds_read_b128 v[156:159], v121 offset:49152
	ds_read_b128 v[160:163], v121 offset:57344
	s_waitcnt lgkmcnt(4)
	v_mfma_f32_32x32x16_bf16 v[50:65], v[132:135], v[140:143], v[50:65]
	s_mov_b32 m0, s37
	s_nop 0
	global_load_lds_dwordx4 v[70:71], off
	v_lshl_add_u64 v[70:71], v[70:71], 0, s[98:99]
	v_mfma_f32_32x32x16_bf16 v[34:49], v[132:135], v[144:147], v[34:49]
	s_add_u32 m0, s37, 0x8000
	s_nop 0
	global_load_lds_dwordx4 v[78:79], off
	v_lshl_add_u64 v[78:79], v[78:79], 0, s[98:99]
	v_mfma_f32_32x32x16_bf16 v[18:33], v[136:139], v[140:143], v[18:33]
	s_add_u32 m0, s37, 0x1000
	s_nop 0
	global_load_lds_dwordx4 v[72:73], off
	v_lshl_add_u64 v[72:73], v[72:73], 0, s[98:99]
	v_mfma_f32_32x32x16_bf16 v[2:17], v[136:139], v[144:147], v[2:17]
	ds_read_b128 v[132:135], v118 offset:16384
	ds_read_b128 v[136:139], v118 offset:20480
	ds_read_b128 v[140:143], v122 offset:49152
	ds_read_b128 v[144:147], v122 offset:57344
	s_waitcnt lgkmcnt(4)
	v_mfma_f32_32x32x16_bf16 v[50:65], v[148:151], v[156:159], v[50:65]
	s_add_u32 m0, s37, 0x9000
	s_nop 0
	global_load_lds_dwordx4 v[80:81], off
	v_lshl_add_u64 v[80:81], v[80:81], 0, s[98:99]
	v_mfma_f32_32x32x16_bf16 v[34:49], v[148:151], v[160:163], v[34:49]
	s_add_u32 m0, s37, 0x2000
	s_nop 0
	global_load_lds_dwordx4 v[74:75], off
	v_lshl_add_u64 v[74:75], v[74:75], 0, s[98:99]
	v_mfma_f32_32x32x16_bf16 v[18:33], v[152:155], v[156:159], v[18:33]
	s_add_u32 m0, s37, 0xa000
	s_nop 0
	global_load_lds_dwordx4 v[82:83], off
	v_lshl_add_u64 v[82:83], v[82:83], 0, s[98:99]
	v_mfma_f32_32x32x16_bf16 v[2:17], v[152:155], v[160:163], v[2:17]
	ds_read_b128 v[148:151], v119 offset:16384
	ds_read_b128 v[152:155], v119 offset:20480
	ds_read_b128 v[156:159], v123 offset:49152
	ds_read_b128 v[160:163], v123 offset:57344
	s_waitcnt lgkmcnt(4)
	v_mfma_f32_32x32x16_bf16 v[50:65], v[132:135], v[140:143], v[50:65]
	s_add_u32 m0, s37, 0x3000
	s_nop 0
	global_load_lds_dwordx4 v[76:77], off
	v_lshl_add_u64 v[76:77], v[76:77], 0, s[98:99]
	v_mfma_f32_32x32x16_bf16 v[34:49], v[132:135], v[144:147], v[34:49]
	s_add_u32 m0, s37, 0xb000
	s_nop 0
	global_load_lds_dwordx4 v[84:85], off
	v_lshl_add_u64 v[84:85], v[84:85], 0, s[98:99]
	v_mfma_f32_32x32x16_bf16 v[18:33], v[136:139], v[140:143], v[18:33]
	v_mfma_f32_32x32x16_bf16 v[2:17], v[136:139], v[144:147], v[2:17]
	s_waitcnt vmcnt(0) lgkmcnt(0)
	s_barrier
	ds_read_b128 v[132:135], v116
	ds_read_b128 v[136:139], v116 offset:4096
	ds_read_b128 v[140:143], v120 offset:32768
	ds_read_b128 v[144:147], v120 offset:40960
	v_mfma_f32_32x32x16_bf16 v[50:65], v[148:151], v[156:159], v[50:65]
	v_mfma_f32_32x32x16_bf16 v[34:49], v[148:151], v[160:163], v[34:49]
	v_mfma_f32_32x32x16_bf16 v[18:33], v[152:155], v[156:159], v[18:33]
	v_mfma_f32_32x32x16_bf16 v[2:17], v[152:155], v[160:163], v[2:17]
	s_sub_u32 s39, s39, 1
	s_cmp_lg_u32 s39, 0
	s_cbranch_scc1 .Lg2_loop
	ds_read_b128 v[148:151], v117
	ds_read_b128 v[152:155], v117 offset:4096
	ds_read_b128 v[156:159], v121 offset:32768
	ds_read_b128 v[160:163], v121 offset:40960
	s_waitcnt lgkmcnt(4)
	v_mfma_f32_32x32x16_bf16 v[50:65], v[132:135], v[140:143], v[50:65]
	s_add_u32 m0, s37, 0x4000
	s_nop 0
	global_load_lds_dwordx4 v[70:71], off
	v_lshl_add_u64 v[70:71], v[70:71], 0, s[98:99]
	v_mfma_f32_32x32x16_bf16 v[34:49], v[132:135], v[144:147], v[34:49]
	s_add_u32 m0, s37, 0xc000
	s_nop 0
	global_load_lds_dwordx4 v[78:79], off
	v_lshl_add_u64 v[78:79], v[78:79], 0, s[98:99]
	v_mfma_f32_32x32x16_bf16 v[18:33], v[136:139], v[140:143], v[18:33]
	s_add_u32 m0, s37, 0x5000
	s_nop 0
	global_load_lds_dwordx4 v[72:73], off
	v_lshl_add_u64 v[72:73], v[72:73], 0, s[98:99]
	v_mfma_f32_32x32x16_bf16 v[2:17], v[136:139], v[144:147], v[2:17]
	ds_read_b128 v[132:135], v118
	ds_read_b128 v[136:139], v118 offset:4096
	ds_read_b128 v[140:143], v122 offset:32768
	ds_read_b128 v[144:147], v122 offset:40960
	s_waitcnt lgkmcnt(4)
	v_mfma_f32_32x32x16_bf16 v[50:65], v[148:151], v[156:159], v[50:65]
	s_add_u32 m0, s37, 0xd000
	s_nop 0
	global_load_lds_dwordx4 v[80:81], off
	v_lshl_add_u64 v[80:81], v[80:81], 0, s[98:99]
	v_mfma_f32_32x32x16_bf16 v[34:49], v[148:151], v[160:163], v[34:49]
	s_add_u32 m0, s37, 0x6000
	s_nop 0
	global_load_lds_dwordx4 v[74:75], off
	v_lshl_add_u64 v[74:75], v[74:75], 0, s[98:99]
	v_mfma_f32_32x32x16_bf16 v[18:33], v[152:155], v[156:159], v[18:33]
	s_add_u32 m0, s37, 0xe000
	s_nop 0
	global_load_lds_dwordx4 v[82:83], off
	v_lshl_add_u64 v[82:83], v[82:83], 0, s[98:99]
	v_mfma_f32_32x32x16_bf16 v[2:17], v[152:155], v[160:163], v[2:17]
	ds_read_b128 v[148:151], v119
	ds_read_b128 v[152:155], v119 offset:4096
	ds_read_b128 v[156:159], v123 offset:32768
	ds_read_b128 v[160:163], v123 offset:40960
	s_waitcnt lgkmcnt(4)
	v_mfma_f32_32x32x16_bf16 v[50:65], v[132:135], v[140:143], v[50:65]
	s_add_u32 m0, s37, 0x7000
	s_nop 0
	global_load_lds_dwordx4 v[76:77], off
	v_lshl_add_u64 v[76:77], v[76:77], 0, s[98:99]
	v_mfma_f32_32x32x16_bf16 v[34:49], v[132:135], v[144:147], v[34:49]
	s_add_u32 m0, s37, 0xf000
	s_nop 0
	global_load_lds_dwordx4 v[84:85], off
	v_lshl_add_u64 v[84:85], v[84:85], 0, s[98:99]
	v_mfma_f32_32x32x16_bf16 v[18:33], v[136:139], v[140:143], v[18:33]
	v_mfma_f32_32x32x16_bf16 v[2:17], v[136:139], v[144:147], v[2:17]
	s_waitcnt vmcnt(0) lgkmcnt(0)
	s_barrier
	ds_read_b128 v[132:135], v116 offset:16384
	ds_read_b128 v[136:139], v116 offset:20480
	ds_read_b128 v[140:143], v120 offset:49152
	ds_read_b128 v[144:147], v120 offset:57344
	v_mfma_f32_32x32x16_bf16 v[50:65], v[148:151], v[156:159], v[50:65]
	v_mfma_f32_32x32x16_bf16 v[34:49], v[148:151], v[160:163], v[34:49]
	v_mfma_f32_32x32x16_bf16 v[18:33], v[152:155], v[156:159], v[18:33]
	v_mfma_f32_32x32x16_bf16 v[2:17], v[152:155], v[160:163], v[2:17]
	ds_read_b128 v[148:151], v117 offset:16384
	ds_read_b128 v[152:155], v117 offset:20480
	ds_read_b128 v[156:159], v121 offset:49152
	ds_read_b128 v[160:163], v121 offset:57344
	s_waitcnt lgkmcnt(4)
	v_mfma_f32_32x32x16_bf16 v[50:65], v[132:135], v[140:143], v[50:65]
	v_mfma_f32_32x32x16_bf16 v[34:49], v[132:135], v[144:147], v[34:49]
	v_mfma_f32_32x32x16_bf16 v[18:33], v[136:139], v[140:143], v[18:33]
	v_mfma_f32_32x32x16_bf16 v[2:17], v[136:139], v[144:147], v[2:17]
	ds_read_b128 v[132:135], v118 offset:16384
	ds_read_b128 v[136:139], v118 offset:20480
	ds_read_b128 v[140:143], v122 offset:49152
	ds_read_b128 v[144:147], v122 offset:57344
	s_waitcnt lgkmcnt(4)
	v_mfma_f32_32x32x16_bf16 v[50:65], v[148:151], v[156:159], v[50:65]
	v_mfma_f32_32x32x16_bf16 v[34:49], v[148:151], v[160:163], v[34:49]
	v_mfma_f32_32x32x16_bf16 v[18:33], v[152:155], v[156:159], v[18:33]
	v_mfma_f32_32x32x16_bf16 v[2:17], v[152:155], v[160:163], v[2:17]
	ds_read_b128 v[148:151], v119 offset:16384
	ds_read_b128 v[152:155], v119 offset:20480
	ds_read_b128 v[156:159], v123 offset:49152
	ds_read_b128 v[160:163], v123 offset:57344
	s_waitcnt lgkmcnt(4)
	v_mfma_f32_32x32x16_bf16 v[50:65], v[132:135], v[140:143], v[50:65]
	v_mfma_f32_32x32x16_bf16 v[34:49], v[132:135], v[144:147], v[34:49]
	v_mfma_f32_32x32x16_bf16 v[18:33], v[136:139], v[140:143], v[18:33]
	v_mfma_f32_32x32x16_bf16 v[2:17], v[136:139], v[144:147], v[2:17]
	s_waitcnt vmcnt(0) lgkmcnt(0)
	s_barrier
	v_mfma_f32_32x32x16_bf16 v[50:65], v[148:151], v[156:159], v[50:65]
	v_mfma_f32_32x32x16_bf16 v[34:49], v[148:151], v[160:163], v[34:49]
	v_mfma_f32_32x32x16_bf16 v[18:33], v[152:155], v[156:159], v[18:33]
	v_mfma_f32_32x32x16_bf16 v[2:17], v[152:155], v[160:163], v[2:17]
	v_or_b32_e32 v70, s38, v91
	v_add_u32_e32 v72, s27, v96
	v_readlane_b32 s38, v253, 18
	s_nop 15
	v_bfe_u32 v73, v50, 16, 1
	v_ashrrev_i32_e32 v71, 31, v70
	v_readlane_b32 s39, v253, 19
	v_add3_u32 v50, v50, v73, s26
	v_ashrrev_i32_e32 v73, 31, v72
	v_lshl_add_u64 v[70:71], v[70:71], 1, s[38:39]
	v_or_b32_e32 v78, 8, v72
	v_ashrrev_i32_e32 v79, 31, v78
	v_lshlrev_b64 v[78:79], 11, v[78:79]
	v_lshl_add_u64 v[78:79], v[70:71], 0, v[78:79]
	v_or_b32_e32 v80, 10, v72
	v_ashrrev_i32_e32 v81, 31, v80
	v_lshlrev_b64 v[74:75], 11, v[72:73]
	v_lshl_add_u64 v[74:75], v[70:71], 0, v[74:75]
	global_store_short_d16_hi v[74:75], v50, off
	v_or_b32_e32 v50, 1, v72
	v_bfe_u32 v73, v51, 16, 1
	v_add3_u32 v73, v51, v73, s26
	v_ashrrev_i32_e32 v51, 31, v50
	v_lshlrev_b64 v[50:51], 11, v[50:51]
	v_or_b32_e32 v76, 2, v72
	v_lshl_add_u64 v[50:51], v[70:71], 0, v[50:51]
	v_ashrrev_i32_e32 v77, 31, v76
	global_store_short_d16_hi v[50:51], v73, off
	v_bfe_u32 v73, v52, 16, 1
	v_lshlrev_b64 v[76:77], 11, v[76:77]
	v_add3_u32 v52, v52, v73, s26
	v_lshl_add_u64 v[76:77], v[70:71], 0, v[76:77]
	global_store_short_d16_hi v[76:77], v52, off
	v_or_b32_e32 v52, 3, v72
	v_bfe_u32 v73, v53, 16, 1
	v_add3_u32 v73, v53, v73, s26
	v_ashrrev_i32_e32 v53, 31, v52
	v_lshlrev_b64 v[52:53], 11, v[52:53]
	v_lshl_add_u64 v[52:53], v[70:71], 0, v[52:53]
	global_store_short_d16_hi v[52:53], v73, off
	v_bfe_u32 v73, v54, 16, 1
	v_add3_u32 v54, v54, v73, s26
	global_store_short_d16_hi v[78:79], v54, off
	v_or_b32_e32 v54, 9, v72
	v_bfe_u32 v73, v55, 16, 1
	v_add3_u32 v73, v55, v73, s26
	v_ashrrev_i32_e32 v55, 31, v54
	v_lshlrev_b64 v[54:55], 11, v[54:55]
	v_lshl_add_u64 v[54:55], v[70:71], 0, v[54:55]
	global_store_short_d16_hi v[54:55], v73, off
	v_bfe_u32 v73, v56, 16, 1
	v_lshlrev_b64 v[80:81], 11, v[80:81]
	v_add3_u32 v56, v56, v73, s26
	v_lshl_add_u64 v[80:81], v[70:71], 0, v[80:81]
	global_store_short_d16_hi v[80:81], v56, off
	v_or_b32_e32 v56, 11, v72
	v_bfe_u32 v73, v57, 16, 1
	v_add3_u32 v73, v57, v73, s26
	v_ashrrev_i32_e32 v57, 31, v56
	v_lshlrev_b64 v[56:57], 11, v[56:57]
	v_or_b32_e32 v82, 16, v72
	v_lshl_add_u64 v[56:57], v[70:71], 0, v[56:57]
	v_ashrrev_i32_e32 v83, 31, v82
	global_store_short_d16_hi v[56:57], v73, off
	v_bfe_u32 v73, v58, 16, 1
	v_lshlrev_b64 v[82:83], 11, v[82:83]
	v_add3_u32 v58, v58, v73, s26
	v_lshl_add_u64 v[82:83], v[70:71], 0, v[82:83]
	global_store_short_d16_hi v[82:83], v58, off
	v_or_b32_e32 v58, 17, v72
	v_bfe_u32 v73, v59, 16, 1
	v_add3_u32 v73, v59, v73, s26
	v_ashrrev_i32_e32 v59, 31, v58
	v_lshlrev_b64 v[58:59], 11, v[58:59]
	v_or_b32_e32 v84, 18, v72
	v_lshl_add_u64 v[58:59], v[70:71], 0, v[58:59]
	v_ashrrev_i32_e32 v85, 31, v84
	global_store_short_d16_hi v[58:59], v73, off
	v_bfe_u32 v73, v60, 16, 1
	v_lshlrev_b64 v[84:85], 11, v[84:85]
	v_add3_u32 v60, v60, v73, s26
	v_lshl_add_u64 v[84:85], v[70:71], 0, v[84:85]
	global_store_short_d16_hi v[84:85], v60, off
	v_or_b32_e32 v60, 19, v72
	v_bfe_u32 v73, v61, 16, 1
	v_add3_u32 v73, v61, v73, s26
	v_ashrrev_i32_e32 v61, 31, v60
	v_lshlrev_b64 v[60:61], 11, v[60:61]
	v_or_b32_e32 v100, 24, v72
	v_lshl_add_u64 v[60:61], v[70:71], 0, v[60:61]
	v_ashrrev_i32_e32 v101, 31, v100
	global_store_short_d16_hi v[60:61], v73, off
	v_bfe_u32 v73, v62, 16, 1
	v_lshlrev_b64 v[100:101], 11, v[100:101]
	v_add3_u32 v62, v62, v73, s26
	v_lshl_add_u64 v[100:101], v[70:71], 0, v[100:101]
	global_store_short_d16_hi v[100:101], v62, off
	v_or_b32_e32 v62, 25, v72
	v_bfe_u32 v73, v63, 16, 1
	v_add3_u32 v73, v63, v73, s26
	v_ashrrev_i32_e32 v63, 31, v62
	v_lshlrev_b64 v[62:63], 11, v[62:63]
	v_or_b32_e32 v102, 26, v72
	v_lshl_add_u64 v[62:63], v[70:71], 0, v[62:63]
	v_ashrrev_i32_e32 v103, 31, v102
	global_store_short_d16_hi v[62:63], v73, off
	v_bfe_u32 v73, v64, 16, 1
	v_lshlrev_b64 v[102:103], 11, v[102:103]
	v_add3_u32 v64, v64, v73, s26
	v_lshl_add_u64 v[102:103], v[70:71], 0, v[102:103]
	global_store_short_d16_hi v[102:103], v64, off
	v_or_b32_e32 v64, 27, v72
	v_bfe_u32 v73, v65, 16, 1
	v_add3_u32 v73, v65, v73, s26
	v_ashrrev_i32_e32 v65, 31, v64
	v_lshlrev_b64 v[64:65], 11, v[64:65]
	v_lshl_add_u64 v[64:65], v[70:71], 0, v[64:65]
	global_store_short_d16_hi v[64:65], v73, off
	v_bfe_u32 v73, v34, 16, 1
	v_add3_u32 v34, v34, v73, s26
	global_store_short_d16_hi v[74:75], v34, off offset:128
	v_bfe_u32 v34, v35, 16, 1
	v_add3_u32 v34, v35, v34, s26
	global_store_short_d16_hi v[50:51], v34, off offset:128
	v_bfe_u32 v34, v36, 16, 1
	v_add3_u32 v34, v36, v34, s26
	global_store_short_d16_hi v[76:77], v34, off offset:128
	v_bfe_u32 v34, v37, 16, 1
	v_add3_u32 v34, v37, v34, s26
	global_store_short_d16_hi v[52:53], v34, off offset:128
	v_bfe_u32 v34, v38, 16, 1
	v_add3_u32 v34, v38, v34, s26
	global_store_short_d16_hi v[78:79], v34, off offset:128
	v_bfe_u32 v34, v39, 16, 1
	v_add3_u32 v34, v39, v34, s26
	global_store_short_d16_hi v[54:55], v34, off offset:128
	v_bfe_u32 v34, v40, 16, 1
	v_add3_u32 v34, v40, v34, s26
	global_store_short_d16_hi v[80:81], v34, off offset:128
	v_bfe_u32 v34, v41, 16, 1
	v_add3_u32 v34, v41, v34, s26
	global_store_short_d16_hi v[56:57], v34, off offset:128
	v_bfe_u32 v34, v42, 16, 1
	v_add3_u32 v34, v42, v34, s26
	global_store_short_d16_hi v[82:83], v34, off offset:128
	v_bfe_u32 v34, v43, 16, 1
	v_add3_u32 v34, v43, v34, s26
	global_store_short_d16_hi v[58:59], v34, off offset:128
	v_bfe_u32 v34, v44, 16, 1
	v_add3_u32 v34, v44, v34, s26
	global_store_short_d16_hi v[84:85], v34, off offset:128
	v_bfe_u32 v34, v45, 16, 1
	v_add3_u32 v34, v45, v34, s26
	global_store_short_d16_hi v[60:61], v34, off offset:128
	v_bfe_u32 v34, v46, 16, 1
	v_add3_u32 v34, v46, v34, s26
	global_store_short_d16_hi v[100:101], v34, off offset:128
	v_bfe_u32 v34, v47, 16, 1
	v_add3_u32 v34, v47, v34, s26
	global_store_short_d16_hi v[62:63], v34, off offset:128
	v_bfe_u32 v34, v48, 16, 1
	v_add3_u32 v34, v48, v34, s26
	global_store_short_d16_hi v[102:103], v34, off offset:128
	v_bfe_u32 v34, v49, 16, 1
	v_add3_u32 v34, v49, v34, s26
	global_store_short_d16_hi v[64:65], v34, off offset:128
	v_or_b32_e32 v34, 32, v72
	v_bfe_u32 v35, v18, 16, 1
	v_add3_u32 v18, v18, v35, s26
	v_ashrrev_i32_e32 v35, 31, v34
	v_lshlrev_b64 v[34:35], 11, v[34:35]
	v_lshl_add_u64 v[34:35], v[70:71], 0, v[34:35]
	global_store_short_d16_hi v[34:35], v18, off
	v_or_b32_e32 v18, 33, v72
	v_bfe_u32 v36, v19, 16, 1
	v_add3_u32 v36, v19, v36, s26
	v_ashrrev_i32_e32 v19, 31, v18
	v_lshlrev_b64 v[18:19], 11, v[18:19]
	v_lshl_add_u64 v[18:19], v[70:71], 0, v[18:19]
	global_store_short_d16_hi v[18:19], v36, off
	v_or_b32_e32 v36, 34, v72
	v_bfe_u32 v37, v20, 16, 1
	v_add3_u32 v20, v20, v37, s26
	v_ashrrev_i32_e32 v37, 31, v36
	v_lshlrev_b64 v[36:37], 11, v[36:37]
	v_lshl_add_u64 v[36:37], v[70:71], 0, v[36:37]
	global_store_short_d16_hi v[36:37], v20, off
	v_or_b32_e32 v20, 35, v72
	v_bfe_u32 v38, v21, 16, 1
	v_add3_u32 v38, v21, v38, s26
	v_ashrrev_i32_e32 v21, 31, v20
	v_lshlrev_b64 v[20:21], 11, v[20:21]
	v_lshl_add_u64 v[20:21], v[70:71], 0, v[20:21]
	global_store_short_d16_hi v[20:21], v38, off
	v_or_b32_e32 v38, 40, v72
	v_bfe_u32 v39, v22, 16, 1
	v_add3_u32 v22, v22, v39, s26
	v_ashrrev_i32_e32 v39, 31, v38
	v_lshlrev_b64 v[38:39], 11, v[38:39]
	v_lshl_add_u64 v[38:39], v[70:71], 0, v[38:39]
	global_store_short_d16_hi v[38:39], v22, off
	v_or_b32_e32 v22, 41, v72
	v_bfe_u32 v40, v23, 16, 1
	v_add3_u32 v40, v23, v40, s26
	v_ashrrev_i32_e32 v23, 31, v22
	v_lshlrev_b64 v[22:23], 11, v[22:23]
	v_lshl_add_u64 v[22:23], v[70:71], 0, v[22:23]
	global_store_short_d16_hi v[22:23], v40, off
	v_or_b32_e32 v40, 42, v72
	v_bfe_u32 v41, v24, 16, 1
	v_add3_u32 v24, v24, v41, s26
	v_ashrrev_i32_e32 v41, 31, v40
	v_lshlrev_b64 v[40:41], 11, v[40:41]
	v_lshl_add_u64 v[40:41], v[70:71], 0, v[40:41]
	global_store_short_d16_hi v[40:41], v24, off
	v_or_b32_e32 v24, 43, v72
	v_bfe_u32 v42, v25, 16, 1
	v_add3_u32 v42, v25, v42, s26
	v_ashrrev_i32_e32 v25, 31, v24
	v_lshlrev_b64 v[24:25], 11, v[24:25]
	v_lshl_add_u64 v[24:25], v[70:71], 0, v[24:25]
	global_store_short_d16_hi v[24:25], v42, off
	v_or_b32_e32 v42, 48, v72
	v_bfe_u32 v43, v26, 16, 1
	v_add3_u32 v26, v26, v43, s26
	v_ashrrev_i32_e32 v43, 31, v42
	v_lshlrev_b64 v[42:43], 11, v[42:43]
	v_lshl_add_u64 v[42:43], v[70:71], 0, v[42:43]
	global_store_short_d16_hi v[42:43], v26, off
	v_or_b32_e32 v26, 49, v72
	v_bfe_u32 v44, v27, 16, 1
	v_add3_u32 v44, v27, v44, s26
	v_ashrrev_i32_e32 v27, 31, v26
	v_lshlrev_b64 v[26:27], 11, v[26:27]
	v_lshl_add_u64 v[26:27], v[70:71], 0, v[26:27]
	global_store_short_d16_hi v[26:27], v44, off
	v_or_b32_e32 v44, 50, v72
	v_bfe_u32 v45, v28, 16, 1
	v_add3_u32 v28, v28, v45, s26
	v_ashrrev_i32_e32 v45, 31, v44
	v_lshlrev_b64 v[44:45], 11, v[44:45]
	v_lshl_add_u64 v[44:45], v[70:71], 0, v[44:45]
	global_store_short_d16_hi v[44:45], v28, off
	v_or_b32_e32 v28, 51, v72
	v_bfe_u32 v46, v29, 16, 1
	v_add3_u32 v46, v29, v46, s26
	v_ashrrev_i32_e32 v29, 31, v28
	v_lshlrev_b64 v[28:29], 11, v[28:29]
	v_lshl_add_u64 v[28:29], v[70:71], 0, v[28:29]
	global_store_short_d16_hi v[28:29], v46, off
	v_or_b32_e32 v46, 56, v72
	v_bfe_u32 v47, v30, 16, 1
	v_add3_u32 v30, v30, v47, s26
	v_ashrrev_i32_e32 v47, 31, v46
	v_lshlrev_b64 v[46:47], 11, v[46:47]
	v_lshl_add_u64 v[46:47], v[70:71], 0, v[46:47]
	global_store_short_d16_hi v[46:47], v30, off
	v_or_b32_e32 v30, 57, v72
	v_bfe_u32 v48, v31, 16, 1
	v_add3_u32 v48, v31, v48, s26
	v_ashrrev_i32_e32 v31, 31, v30
	v_lshlrev_b64 v[30:31], 11, v[30:31]
	v_lshl_add_u64 v[30:31], v[70:71], 0, v[30:31]
	global_store_short_d16_hi v[30:31], v48, off
	v_or_b32_e32 v48, 58, v72
	v_bfe_u32 v49, v32, 16, 1
	v_add3_u32 v32, v32, v49, s26
	v_ashrrev_i32_e32 v49, 31, v48
	v_lshlrev_b64 v[48:49], 11, v[48:49]
	v_lshl_add_u64 v[48:49], v[70:71], 0, v[48:49]
	global_store_short_d16_hi v[48:49], v32, off
	v_or_b32_e32 v32, 59, v72
	v_bfe_u32 v50, v33, 16, 1
	v_add3_u32 v50, v33, v50, s26
	v_ashrrev_i32_e32 v33, 31, v32
	v_lshlrev_b64 v[32:33], 11, v[32:33]
	v_lshl_add_u64 v[32:33], v[70:71], 0, v[32:33]
	global_store_short_d16_hi v[32:33], v50, off
	v_bfe_u32 v50, v2, 16, 1
	v_add3_u32 v2, v2, v50, s26
	global_store_short_d16_hi v[34:35], v2, off offset:128
	v_bfe_u32 v2, v3, 16, 1
	v_add3_u32 v2, v3, v2, s26
	global_store_short_d16_hi v[18:19], v2, off offset:128
	v_bfe_u32 v2, v4, 16, 1
	v_add3_u32 v2, v4, v2, s26
	global_store_short_d16_hi v[36:37], v2, off offset:128
	v_bfe_u32 v2, v5, 16, 1
	v_add3_u32 v2, v5, v2, s26
	global_store_short_d16_hi v[20:21], v2, off offset:128
	v_bfe_u32 v2, v6, 16, 1
	v_add3_u32 v2, v6, v2, s26
	global_store_short_d16_hi v[38:39], v2, off offset:128
	v_bfe_u32 v2, v7, 16, 1
	v_add3_u32 v2, v7, v2, s26
	global_store_short_d16_hi v[22:23], v2, off offset:128
	v_bfe_u32 v2, v8, 16, 1
	v_add3_u32 v2, v8, v2, s26
	global_store_short_d16_hi v[40:41], v2, off offset:128
	v_bfe_u32 v2, v9, 16, 1
	v_add3_u32 v2, v9, v2, s26
	global_store_short_d16_hi v[24:25], v2, off offset:128
	v_bfe_u32 v2, v10, 16, 1
	v_add3_u32 v2, v10, v2, s26
	global_store_short_d16_hi v[42:43], v2, off offset:128
	v_bfe_u32 v2, v11, 16, 1
	v_add3_u32 v2, v11, v2, s26
	global_store_short_d16_hi v[26:27], v2, off offset:128
	v_bfe_u32 v2, v12, 16, 1
	v_add3_u32 v2, v12, v2, s26
	global_store_short_d16_hi v[44:45], v2, off offset:128
	v_bfe_u32 v2, v13, 16, 1
	v_add3_u32 v2, v13, v2, s26
	global_store_short_d16_hi v[28:29], v2, off offset:128
	v_bfe_u32 v2, v14, 16, 1
	v_add3_u32 v2, v14, v2, s26
	global_store_short_d16_hi v[46:47], v2, off offset:128
	v_bfe_u32 v2, v15, 16, 1
	v_add3_u32 v2, v15, v2, s26
	global_store_short_d16_hi v[30:31], v2, off offset:128
	v_bfe_u32 v2, v16, 16, 1
	v_add3_u32 v2, v16, v2, s26
	global_store_short_d16_hi v[48:49], v2, off offset:128
	v_bfe_u32 v2, v17, 16, 1
	v_add3_u32 v2, v17, v2, s26
	v_readlane_b32 s38, v252, 2
	global_store_short_d16_hi v[32:33], v2, off offset:128
	v_readlane_b32 s39, v252, 3
	s_load_dword s11, s[38:39], 0x0
	s_waitcnt lgkmcnt(0)
	s_add_i32 s16, s11, s16
	s_cmpk_gt_i32 s16, 0x1ff
	s_cbranch_scc0 .LBB0_88
